# v24 (HGRN chain at raised wave priority) + GEMM-phase start stagger of the second co-resident block lengthened from s_sleep 12 to s_sleep 24
# baseline (speedup 1.0000x reference)
.LBB0_25:
	s_mov_b64 s[20:21], 0
	v_writelane_b32 v232, s20, 29
	s_mov_b64 s[0:1], -1
	s_mov_b64 s[48:49], 0
	s_cmp_lt_i32 s62, 4
	v_writelane_b32 v232, s21, 30
	v_writelane_b32 v232, s62, 31
	s_cbranch_scc1 .LBB0_154
	s_cmp_gt_i32 s62, 5
	s_cbranch_scc0 .LBB0_43
	s_cmp_gt_i32 s62, 6
	s_cbranch_scc0 .LBB0_44
	s_cmp_gt_i32 s62, 7
	s_cbranch_scc0 .LBB0_46
	s_cmp_eq_u32 s62, 8
	s_cbranch_scc0 .LBB0_42
	v_readlane_b32 s0, v235, 0
	s_bitcmp0_b32 s0, 8
	s_cbranch_scc1 .LBB0_32
	s_sleep 24

.LBB0_46:
	s_mov_b64 s[20:21], 0
	v_writelane_b32 v232, s20, 29
	s_nop 1
	v_writelane_b32 v232, s21, 30
	s_and_b64 vcc, exec, s[0:1]
	s_cbranch_vccz .LBB0_58
	v_readlane_b32 s0, v235, 0
	s_bitcmp0_b32 s0, 8
	s_cbranch_scc1 .LBB0_49
	s_sleep 24

.LBB0_65:
	s_cmp_gt_i32 s62, 4
	s_mov_b64 s[0:1], -1
	s_cbranch_scc0 .LBB0_149
	v_readlane_b32 s0, v235, 0
	s_bitcmp0_b32 s0, 8
	s_cbranch_scc1 .LBB0_68
	s_sleep 24

.LBB0_793:
	v_readlane_b32 s66, v235, 56
	s_andn2_b64 vcc, exec, s[0:1]
	v_readlane_b32 s67, v235, 57
	s_cbranch_vccnz .LBB0_1083
	v_readlane_b32 s0, v235, 0
	s_bitcmp0_b32 s0, 8
	s_cbranch_scc1 .LBB0_796
	s_sleep 24

.LBB0_1180:
	s_andn2_b64 vcc, exec, s[48:49]
	s_cbranch_vccnz .LBB0_1746
	v_readlane_b32 s20, v235, 0
	s_bitcmp0_b32 s20, 8
	s_cbranch_scc1 .LBB0_1183
	s_sleep 24
